# inproj0: each block walks its 7 tile pairs starting so that the pair with the lightest epilogue (u tiles) comes last (shorter phase tail); same pairs per block
# speedup vs baseline: 1.0050x; 1.0039x over previous
.LBB0_168:
	s_or_b64 exec, exec, s[0:1]
	s_add_u32 s36, s50, 0x5a00000
	s_addc_u32 s37, s51, 0
	s_add_u32 s0, s50, 0xda00000
	v_writelane_b32 v247, s0, 3
	s_addc_u32 s0, s51, 0
	v_bfe_u32 v134, v131, 4, 2
	v_bfe_u32 v139, v131, 1, 3
	s_cmpk_gt_i32 s2, 0x1bff
	v_and_b32_e32 v138, 15, v131
	v_lshlrev_b32_e32 v149, 8, v131
	v_lshrrev_b32_e32 v153, 1, v131
	v_or_b32_e32 v136, 4, v134
	v_bitop3_b32 v152, v134, v139, 4 bitop3:0x36
	v_lshlrev_b32_e32 v137, 9, v134
	v_or_b32_e32 v132, 8, v134
	v_or_b32_e32 v130, 12, v134
	s_waitcnt lgkmcnt(0)
	s_barrier
	v_writelane_b32 v247, s0, 4
	s_cbranch_scc1 .LBB0_196
	v_xor_b32_e32 v0, v128, v131
	v_and_b32_e32 v142, 0x3f800, v149
	v_mov_b32_e32 v143, 0
	v_lshlrev_b32_e32 v0, 4, v0
	v_and_b32_e32 v0, 0x70, v0
	v_mov_b32_e32 v1, v143
	v_lshl_add_u64 v[2:3], s[50:51], 0, v[142:143]
	v_lshl_add_u64 v[0:1], v[2:3], 0, v[0:1]
	s_mov_b64 s[0:1], 0x3a00000
	v_lshl_add_u64 v[144:145], v[0:1], 0, s[0:1]
	s_mov_b64 s[0:1], 0x1a00000
	v_lshl_add_u64 v[146:147], v[0:1], 0, s[0:1]
	s_movk_i32 s0, 0x1e0
	v_and_or_b32 v0, v153, s0, v138
	v_bitop3_b32 v1, v128, v139, 3 bitop3:0x6c
	v_lshlrev_b32_e32 v159, 7, v0
	v_lshlrev_b32_e32 v0, 13, v135
	v_lshlrev_b32_e32 v158, 4, v1
	v_lshl_add_u32 v1, v134, 3, v138
	v_lshl_or_b32 v2, v134, 11, v0
	v_lshlrev_b32_e32 v4, 5, v138
	v_or3_b32 v161, v0, v137, v4
	v_lshl_or_b32 v162, v1, 2, v2
	v_add_u32_e32 v4, 0x60, v1
	v_add_u32_e32 v1, 0x70, v1
	v_and_b32_e32 v4, 0x7f, v4
	v_and_b32_e32 v1, 0x7f, v1
	v_lshl_or_b32 v163, v4, 2, v2
	v_lshl_or_b32 v164, v1, 2, v2
	v_add_u32_e32 v2, 8, v133
	v_and_b32_e32 v2, 0x78, v2
	v_lshlrev_b32_e32 v1, 9, v136
	v_lshlrev_b32_e32 v2, 2, v2
	v_or3_b32 v166, v0, v1, v2
	v_add_u32_e32 v2, 16, v133
	v_and_b32_e32 v2, 0x78, v2
	v_lshlrev_b32_e32 v1, 9, v132
	v_lshlrev_b32_e32 v2, 2, v2
	v_or3_b32 v168, v0, v1, v2
	v_add_u32_e32 v2, 24, v133
	v_and_b32_e32 v2, 0x78, v2
	v_lshlrev_b32_e32 v3, 5, v135
	v_lshlrev_b32_e32 v1, 9, v130
	v_lshlrev_b32_e32 v2, 2, v2
	v_or3_b32 v170, v0, v1, v2
	v_or_b32_e32 v0, 16, v3
	v_add_u32_e32 v4, 0x100, v131
	v_add_u32_e32 v5, 0x200, v131
	v_add_u32_e32 v6, 0x300, v131
	v_add_u32_e32 v7, 0x500, v131
	v_add_u32_e32 v8, 0x600, v131
	v_add_u32_e32 v9, 0x700, v131
	v_or_b32_e32 v172, v0, v134
	v_or_b32_e32 v173, v136, v0
	v_or_b32_e32 v174, v132, v0
	v_or_b32_e32 v175, v130, v0
	v_and_b32_e32 v0, 24, v153
	s_movk_i32 s0, 0x3c0
	v_lshrrev_b32_e32 v176, 4, v4
	v_lshrrev_b32_e32 v177, 4, v5
	v_lshrrev_b32_e32 v178, 4, v6
	v_lshrrev_b32_e32 v180, 4, v7
	v_lshrrev_b32_e32 v181, 4, v8
	v_lshrrev_b32_e32 v182, 4, v9
	v_bitop3_b32 v10, v128, 7, v131 bitop3:0x48
	v_or_b32_e32 v165, v134, v3
	v_or_b32_e32 v167, v136, v3
	v_or_b32_e32 v169, v132, v3
	v_or_b32_e32 v171, v130, v3
	v_and_or_b32 v0, v131, s0, v0
	v_mul_u32_u24_e32 v1, 0x110, v138
	v_lshlrev_b32_e32 v2, 4, v138
	v_mul_u32_u24_e32 v3, 0x110, v128
	v_mul_u32_u24_e32 v4, 0x110, v176
	v_mul_u32_u24_e32 v5, 0x110, v177
	v_mul_u32_u24_e32 v6, 0x110, v178
	v_mul_u32_u24_e32 v7, 0x110, v180
	v_mul_u32_u24_e32 v8, 0x110, v181
	v_mul_u32_u24_e32 v9, 0x110, v182
	s_add_u32 s33, s48, 0x2000000
	v_lshl_or_b32 v142, v10, 4, v142
	v_lshlrev_b32_e32 v156, 7, v138
	v_lshlrev_b32_e32 v160, 4, v152
	v_lshlrev_b32_e32 v148, 3, v138
	v_or_b32_e32 v179, 64, v128
	s_addc_u32 s39, s49, 0
	v_lshl_add_u64 v[150:151], s[50:51], 0, v[142:143]
	s_mov_b64 s[8:9], 0x10000
	v_add_u32_e32 v183, 0x1000, v129
	s_mov_b64 s[10:11], 0x20000
	v_add_u32_e32 v184, 0x2000, v129
	s_mov_b64 s[12:13], 0x30000
	v_add_u32_e32 v185, 0x3000, v129
	v_or_b32_e32 v186, 0x4000, v129
	v_add_u32_e32 v187, 0x5000, v129
	v_add_u32_e32 v188, 0x6000, v129
	v_add_u32_e32 v189, 0x7000, v129
	s_mov_b64 s[14:15], 0x3a00080
	s_mov_b64 s[16:17], 0x3a10080
	s_mov_b64 s[18:19], 0x3a20080
	s_mov_b64 s[20:21], 0x3a30080
	s_mov_b64 s[22:23], 0x1a00080
	s_mov_b64 s[24:25], 0x1a10080
	s_mov_b64 s[28:29], 0x1a20080
	s_mov_b64 s[30:31], 0x1a30080
	s_mov_b32 s35, 0
	v_lshlrev_b32_e32 v190, 2, v138
	s_brev_b32 s38, 60
	s_mov_b32 s46, 0x358637bd
	s_mov_b32 s47, 0x800000
	s_mov_b32 s52, 0x45800000
	s_mov_b32 s60, 0x3e0293ee
	s_mov_b32 s53, 0x9a00000
	s_movk_i32 s61, 0x7fff
	s_mov_b32 s74, 0x7060302
	v_add_u32_e32 v191, v0, v1
	v_add_u32_e32 v192, v2, v3
	v_add_u32_e32 v193, v2, v4
	v_add_u32_e32 v194, v2, v5
	v_add_u32_e32 v195, v2, v6
	v_add_u32_e32 v196, v2, v7
	v_add_u32_e32 v197, v2, v8
	v_add_u32_e32 v198, v2, v9
	v_mbcnt_hi_u32_b32 v199, -1, v155
	s_mov_b32 s75, s2
	s_mov_b32 s89, 0
	s_mov_b32 s95, -1
	s_cmp_eq_u32 s3, 0x200
	s_cbranch_scc0 .LBB0_171
	s_and_b32 s94, s2, 7
	s_lshr_b32 s95, s2, 8
	s_add_i32 s94, s94, s95
	s_mul_i32 s94, s94, 3
	s_sub_i32 s95, s94, 7
	s_cmp_ge_i32 s94, 7
	s_cselect_b32 s94, s95, s94
	s_sub_i32 s95, s94, 7
	s_cmp_ge_i32 s94, 7
	s_cselect_b32 s94, s95, s94
	s_sub_i32 s95, s94, 7
	s_cmp_ge_i32 s94, 7
	s_cselect_b32 s94, s95, s94
	s_add_i32 s94, s94, 1
	s_cmp_eq_u32 s94, 7
	s_cselect_b32 s94, 0, s94
	s_lshl_b32 s94, s94, 9
	s_add_i32 s75, s2, s94
	s_mov_b32 s95, s75
	s_branch .LBB0_171
.LBB0_170:
	s_xor_b32 s89, s89, 1
	s_cmp_lg_u32 s89, 0
	s_cbranch_scc1 .LBB0_171
	s_add_i32 s75, s75, s3
	s_cmp_lt_i32 s95, 0
	s_cbranch_scc1 .Lmy_ip0_lin
	s_cmpk_lt_i32 s75, 0xe00
	s_cbranch_scc1 .Lmy_ip0_nw
	s_sub_i32 s75, s75, 0xe00
.Lmy_ip0_nw:
	s_cmp_eq_u32 s75, s95
	s_cbranch_scc1 .LBB0_196
	s_branch .LBB0_171
.Lmy_ip0_lin:
	s_cmpk_lt_i32 s75, 0xe00
	s_cbranch_scc0 .LBB0_196
